# swiglu epilogue re-emitted in four batches (transcendentals in runs, long dependency distances), on top of serpentine accumulate-chain MFMA order
# speedup vs baseline: 1.0224x; 1.0001x over previous
.LBB0_377:
	v_lshl_add_u32 v148, s26, 8, v144
	v_lshl_or_b32 v142, s24, 7, v146
	v_ashrrev_i32_e32 v143, 31, v142
	v_mov_b64_e32 v[140:141], s[6:7]
	v_lshlrev_b64 v[142:143], 1, v[142:143]
	s_nop 3
	v_pk_mul_f32 v[126:127], v[126:127], v[122:123]
	v_pk_mul_f32 v[128:129], v[128:129], v[124:125]
	v_pk_mul_f32 v[118:119], v[118:119], v[114:115]
	v_pk_mul_f32 v[120:121], v[120:121], v[116:117]
	v_pk_mul_f32 v[110:111], v[110:111], v[106:107]
	v_pk_mul_f32 v[112:113], v[112:113], v[108:109]
	v_pk_mul_f32 v[102:103], v[102:103], v[98:99]
	v_pk_mul_f32 v[104:105], v[104:105], v[100:101]
	v_pk_mul_f32 v[122:123], v[122:123], v[250:251] op_sel_hi:[1,0]
	v_pk_mul_f32 v[124:125], v[124:125], v[250:251] op_sel_hi:[1,0]
	v_pk_mul_f32 v[114:115], v[114:115], v[250:251] op_sel_hi:[1,0]
	v_pk_mul_f32 v[116:117], v[116:117], v[250:251] op_sel_hi:[1,0]
	v_pk_mul_f32 v[106:107], v[106:107], v[250:251] op_sel_hi:[1,0]
	v_pk_mul_f32 v[108:109], v[108:109], v[250:251] op_sel_hi:[1,0]
	v_pk_mul_f32 v[98:99], v[98:99], v[250:251] op_sel_hi:[1,0]
	v_pk_mul_f32 v[100:101], v[100:101], v[250:251] op_sel_hi:[1,0]
	v_exp_f32_e32 v122, v122
	v_exp_f32_e32 v123, v123
	v_exp_f32_e32 v124, v124
	v_exp_f32_e32 v125, v125
	v_exp_f32_e32 v114, v114
	v_exp_f32_e32 v115, v115
	v_exp_f32_e32 v116, v116
	v_exp_f32_e32 v117, v117
	v_exp_f32_e32 v106, v106
	v_exp_f32_e32 v107, v107
	v_exp_f32_e32 v108, v108
	v_exp_f32_e32 v109, v109
	v_exp_f32_e32 v98, v98
	v_exp_f32_e32 v99, v99
	v_exp_f32_e32 v100, v100
	v_exp_f32_e32 v101, v101
	v_pk_add_f32 v[122:123], v[122:123], 1.0 op_sel_hi:[1,0]
	v_pk_add_f32 v[124:125], v[124:125], 1.0 op_sel_hi:[1,0]
	v_pk_add_f32 v[114:115], v[114:115], 1.0 op_sel_hi:[1,0]
	v_pk_add_f32 v[116:117], v[116:117], 1.0 op_sel_hi:[1,0]
	v_pk_add_f32 v[106:107], v[106:107], 1.0 op_sel_hi:[1,0]
	v_pk_add_f32 v[108:109], v[108:109], 1.0 op_sel_hi:[1,0]
	v_pk_add_f32 v[98:99], v[98:99], 1.0 op_sel_hi:[1,0]
	v_pk_add_f32 v[100:101], v[100:101], 1.0 op_sel_hi:[1,0]
	v_rcp_f32_e32 v122, v122
	v_rcp_f32_e32 v123, v123
	v_rcp_f32_e32 v124, v124
	v_rcp_f32_e32 v125, v125
	v_rcp_f32_e32 v114, v114
	v_rcp_f32_e32 v115, v115
	v_rcp_f32_e32 v116, v116
	v_rcp_f32_e32 v117, v117
	v_rcp_f32_e32 v106, v106
	v_rcp_f32_e32 v107, v107
	v_rcp_f32_e32 v108, v108
	v_rcp_f32_e32 v109, v109
	v_rcp_f32_e32 v98, v98
	v_rcp_f32_e32 v99, v99
	v_rcp_f32_e32 v100, v100
	v_rcp_f32_e32 v101, v101
	v_pk_mul_f32 v[126:127], v[126:127], v[122:123]
	v_pk_mul_f32 v[128:129], v[128:129], v[124:125]
	v_pk_mul_f32 v[118:119], v[118:119], v[114:115]
	v_pk_mul_f32 v[120:121], v[120:121], v[116:117]
	v_pk_mul_f32 v[110:111], v[110:111], v[106:107]
	v_pk_mul_f32 v[112:113], v[112:113], v[108:109]
	v_pk_mul_f32 v[102:103], v[102:103], v[98:99]
	v_pk_mul_f32 v[104:105], v[104:105], v[100:101]
	v_mov_b32_e32 v150, v148
	v_mad_i64_i32 v[150:151], s[24:25], v150, s86, v[140:141]
	v_cvt_pk_bf16_f32 v156, v126, v127
	v_cvt_pk_bf16_f32 v157, v128, v129
	v_cvt_pk_bf16_f32 v158, v118, v119
	v_cvt_pk_bf16_f32 v159, v120, v121
	v_lshl_add_u64 v[150:151], v[150:151], 0, v[142:143]
	global_store_dwordx4 v[150:151], v[156:159], off
	v_or_b32_e32 v152, 16, v148
	v_mad_i64_i32 v[152:153], s[24:25], v152, s86, v[140:141]
	v_cvt_pk_bf16_f32 v160, v110, v111
	v_cvt_pk_bf16_f32 v161, v112, v113
	v_cvt_pk_bf16_f32 v162, v102, v103
	v_cvt_pk_bf16_f32 v163, v104, v105
	v_lshl_add_u64 v[152:153], v[152:153], 0, v[142:143]
	global_store_dwordx4 v[152:153], v[160:163], off
	v_pk_mul_f32 v[94:95], v[94:95], v[90:91]
	v_pk_mul_f32 v[96:97], v[96:97], v[92:93]
	v_pk_mul_f32 v[86:87], v[86:87], v[82:83]
	v_pk_mul_f32 v[88:89], v[88:89], v[84:85]
	v_pk_mul_f32 v[78:79], v[78:79], v[74:75]
	v_pk_mul_f32 v[80:81], v[80:81], v[76:77]
	v_pk_mul_f32 v[70:71], v[70:71], v[66:67]
	v_pk_mul_f32 v[72:73], v[72:73], v[68:69]
	v_pk_mul_f32 v[90:91], v[90:91], v[250:251] op_sel_hi:[1,0]
	v_pk_mul_f32 v[92:93], v[92:93], v[250:251] op_sel_hi:[1,0]
	v_pk_mul_f32 v[82:83], v[82:83], v[250:251] op_sel_hi:[1,0]
	v_pk_mul_f32 v[84:85], v[84:85], v[250:251] op_sel_hi:[1,0]
	v_pk_mul_f32 v[74:75], v[74:75], v[250:251] op_sel_hi:[1,0]
	v_pk_mul_f32 v[76:77], v[76:77], v[250:251] op_sel_hi:[1,0]
	v_pk_mul_f32 v[66:67], v[66:67], v[250:251] op_sel_hi:[1,0]
	v_pk_mul_f32 v[68:69], v[68:69], v[250:251] op_sel_hi:[1,0]
	v_exp_f32_e32 v90, v90
	v_exp_f32_e32 v91, v91
	v_exp_f32_e32 v92, v92
	v_exp_f32_e32 v93, v93
	v_exp_f32_e32 v82, v82
	v_exp_f32_e32 v83, v83
	v_exp_f32_e32 v84, v84
	v_exp_f32_e32 v85, v85
	v_exp_f32_e32 v74, v74
	v_exp_f32_e32 v75, v75
	v_exp_f32_e32 v76, v76
	v_exp_f32_e32 v77, v77
	v_exp_f32_e32 v66, v66
	v_exp_f32_e32 v67, v67
	v_exp_f32_e32 v68, v68
	v_exp_f32_e32 v69, v69
	v_pk_add_f32 v[90:91], v[90:91], 1.0 op_sel_hi:[1,0]
	v_pk_add_f32 v[92:93], v[92:93], 1.0 op_sel_hi:[1,0]
	v_pk_add_f32 v[82:83], v[82:83], 1.0 op_sel_hi:[1,0]
	v_pk_add_f32 v[84:85], v[84:85], 1.0 op_sel_hi:[1,0]
	v_pk_add_f32 v[74:75], v[74:75], 1.0 op_sel_hi:[1,0]
	v_pk_add_f32 v[76:77], v[76:77], 1.0 op_sel_hi:[1,0]
	v_pk_add_f32 v[66:67], v[66:67], 1.0 op_sel_hi:[1,0]
	v_pk_add_f32 v[68:69], v[68:69], 1.0 op_sel_hi:[1,0]
	v_rcp_f32_e32 v90, v90
	v_rcp_f32_e32 v91, v91
	v_rcp_f32_e32 v92, v92
	v_rcp_f32_e32 v93, v93
	v_rcp_f32_e32 v82, v82
	v_rcp_f32_e32 v83, v83
	v_rcp_f32_e32 v84, v84
	v_rcp_f32_e32 v85, v85
	v_rcp_f32_e32 v74, v74
	v_rcp_f32_e32 v75, v75
	v_rcp_f32_e32 v76, v76
	v_rcp_f32_e32 v77, v77
	v_rcp_f32_e32 v66, v66
	v_rcp_f32_e32 v67, v67
	v_rcp_f32_e32 v68, v68
	v_rcp_f32_e32 v69, v69
	v_pk_mul_f32 v[94:95], v[94:95], v[90:91]
	v_pk_mul_f32 v[96:97], v[96:97], v[92:93]
	v_pk_mul_f32 v[86:87], v[86:87], v[82:83]
	v_pk_mul_f32 v[88:89], v[88:89], v[84:85]
	v_pk_mul_f32 v[78:79], v[78:79], v[74:75]
	v_pk_mul_f32 v[80:81], v[80:81], v[76:77]
	v_pk_mul_f32 v[70:71], v[70:71], v[66:67]
	v_pk_mul_f32 v[72:73], v[72:73], v[68:69]
	v_or_b32_e32 v154, 32, v148
	v_mad_i64_i32 v[154:155], s[24:25], v154, s86, v[140:141]
	v_cvt_pk_bf16_f32 v156, v94, v95
	v_cvt_pk_bf16_f32 v157, v96, v97
	v_cvt_pk_bf16_f32 v158, v86, v87
	v_cvt_pk_bf16_f32 v159, v88, v89
	v_lshl_add_u64 v[154:155], v[154:155], 0, v[142:143]
	global_store_dwordx4 v[154:155], v[156:159], off
	v_or_b32_e32 v150, 48, v148
	v_mad_i64_i32 v[150:151], s[24:25], v150, s86, v[140:141]
	v_cvt_pk_bf16_f32 v160, v78, v79
	v_cvt_pk_bf16_f32 v161, v80, v81
	v_cvt_pk_bf16_f32 v162, v70, v71
	v_cvt_pk_bf16_f32 v163, v72, v73
	v_lshl_add_u64 v[150:151], v[150:151], 0, v[142:143]
	global_store_dwordx4 v[150:151], v[160:163], off
	v_pk_mul_f32 v[62:63], v[62:63], v[58:59]
	v_pk_mul_f32 v[64:65], v[64:65], v[60:61]
	v_pk_mul_f32 v[54:55], v[54:55], v[50:51]
	v_pk_mul_f32 v[56:57], v[56:57], v[52:53]
	v_pk_mul_f32 v[46:47], v[46:47], v[42:43]
	v_pk_mul_f32 v[48:49], v[48:49], v[44:45]
	v_pk_mul_f32 v[38:39], v[38:39], v[34:35]
	v_pk_mul_f32 v[40:41], v[40:41], v[36:37]
	v_pk_mul_f32 v[58:59], v[58:59], v[250:251] op_sel_hi:[1,0]
	v_pk_mul_f32 v[60:61], v[60:61], v[250:251] op_sel_hi:[1,0]
	v_pk_mul_f32 v[50:51], v[50:51], v[250:251] op_sel_hi:[1,0]
	v_pk_mul_f32 v[52:53], v[52:53], v[250:251] op_sel_hi:[1,0]
	v_pk_mul_f32 v[42:43], v[42:43], v[250:251] op_sel_hi:[1,0]
	v_pk_mul_f32 v[44:45], v[44:45], v[250:251] op_sel_hi:[1,0]
	v_pk_mul_f32 v[34:35], v[34:35], v[250:251] op_sel_hi:[1,0]
	v_pk_mul_f32 v[36:37], v[36:37], v[250:251] op_sel_hi:[1,0]
	v_exp_f32_e32 v58, v58
	v_exp_f32_e32 v59, v59
	v_exp_f32_e32 v60, v60
	v_exp_f32_e32 v61, v61
	v_exp_f32_e32 v50, v50
	v_exp_f32_e32 v51, v51
	v_exp_f32_e32 v52, v52
	v_exp_f32_e32 v53, v53
	v_exp_f32_e32 v42, v42
	v_exp_f32_e32 v43, v43
	v_exp_f32_e32 v44, v44
	v_exp_f32_e32 v45, v45
	v_exp_f32_e32 v34, v34
	v_exp_f32_e32 v35, v35
	v_exp_f32_e32 v36, v36
	v_exp_f32_e32 v37, v37
	v_pk_add_f32 v[58:59], v[58:59], 1.0 op_sel_hi:[1,0]
	v_pk_add_f32 v[60:61], v[60:61], 1.0 op_sel_hi:[1,0]
	v_pk_add_f32 v[50:51], v[50:51], 1.0 op_sel_hi:[1,0]
	v_pk_add_f32 v[52:53], v[52:53], 1.0 op_sel_hi:[1,0]
	v_pk_add_f32 v[42:43], v[42:43], 1.0 op_sel_hi:[1,0]
	v_pk_add_f32 v[44:45], v[44:45], 1.0 op_sel_hi:[1,0]
	v_pk_add_f32 v[34:35], v[34:35], 1.0 op_sel_hi:[1,0]
	v_pk_add_f32 v[36:37], v[36:37], 1.0 op_sel_hi:[1,0]
	v_rcp_f32_e32 v58, v58
	v_rcp_f32_e32 v59, v59
	v_rcp_f32_e32 v60, v60
	v_rcp_f32_e32 v61, v61
	v_rcp_f32_e32 v50, v50
	v_rcp_f32_e32 v51, v51
	v_rcp_f32_e32 v52, v52
	v_rcp_f32_e32 v53, v53
	v_rcp_f32_e32 v42, v42
	v_rcp_f32_e32 v43, v43
	v_rcp_f32_e32 v44, v44
	v_rcp_f32_e32 v45, v45
	v_rcp_f32_e32 v34, v34
	v_rcp_f32_e32 v35, v35
	v_rcp_f32_e32 v36, v36
	v_rcp_f32_e32 v37, v37
	v_pk_mul_f32 v[62:63], v[62:63], v[58:59]
	v_pk_mul_f32 v[64:65], v[64:65], v[60:61]
	v_pk_mul_f32 v[54:55], v[54:55], v[50:51]
	v_pk_mul_f32 v[56:57], v[56:57], v[52:53]
	v_pk_mul_f32 v[46:47], v[46:47], v[42:43]
	v_pk_mul_f32 v[48:49], v[48:49], v[44:45]
	v_pk_mul_f32 v[38:39], v[38:39], v[34:35]
	v_pk_mul_f32 v[40:41], v[40:41], v[36:37]
	v_add_u32_e32 v152, 0x80, v148
	v_mad_i64_i32 v[152:153], s[24:25], v152, s86, v[140:141]
	v_cvt_pk_bf16_f32 v156, v62, v63
	v_cvt_pk_bf16_f32 v157, v64, v65
	v_cvt_pk_bf16_f32 v158, v54, v55
	v_cvt_pk_bf16_f32 v159, v56, v57
	v_lshl_add_u64 v[152:153], v[152:153], 0, v[142:143]
	global_store_dwordx4 v[152:153], v[156:159], off
	v_add_u32_e32 v154, 0x90, v148
	v_mad_i64_i32 v[154:155], s[24:25], v154, s86, v[140:141]
	v_cvt_pk_bf16_f32 v160, v46, v47
	v_cvt_pk_bf16_f32 v161, v48, v49
	v_cvt_pk_bf16_f32 v162, v38, v39
	v_cvt_pk_bf16_f32 v163, v40, v41
	v_lshl_add_u64 v[154:155], v[154:155], 0, v[142:143]
	global_store_dwordx4 v[154:155], v[160:163], off
	v_pk_mul_f32 v[30:31], v[30:31], v[26:27]
	v_pk_mul_f32 v[32:33], v[32:33], v[28:29]
	v_pk_mul_f32 v[22:23], v[22:23], v[18:19]
	v_pk_mul_f32 v[24:25], v[24:25], v[20:21]
	v_pk_mul_f32 v[14:15], v[14:15], v[10:11]
	v_pk_mul_f32 v[16:17], v[16:17], v[12:13]
	v_pk_mul_f32 v[2:3], v[2:3], v[6:7]
	v_pk_mul_f32 v[4:5], v[4:5], v[8:9]
	v_pk_mul_f32 v[26:27], v[26:27], v[250:251] op_sel_hi:[1,0]
	v_pk_mul_f32 v[28:29], v[28:29], v[250:251] op_sel_hi:[1,0]
	v_pk_mul_f32 v[18:19], v[18:19], v[250:251] op_sel_hi:[1,0]
	v_pk_mul_f32 v[20:21], v[20:21], v[250:251] op_sel_hi:[1,0]
	v_pk_mul_f32 v[10:11], v[10:11], v[250:251] op_sel_hi:[1,0]
	v_pk_mul_f32 v[12:13], v[12:13], v[250:251] op_sel_hi:[1,0]
	v_pk_mul_f32 v[6:7], v[6:7], v[250:251] op_sel_hi:[1,0]
	v_pk_mul_f32 v[8:9], v[8:9], v[250:251] op_sel_hi:[1,0]
	v_exp_f32_e32 v26, v26
	v_exp_f32_e32 v27, v27
	v_exp_f32_e32 v28, v28
	v_exp_f32_e32 v29, v29
	v_exp_f32_e32 v18, v18
	v_exp_f32_e32 v19, v19
	v_exp_f32_e32 v20, v20
	v_exp_f32_e32 v21, v21
	v_exp_f32_e32 v10, v10
	v_exp_f32_e32 v11, v11
	v_exp_f32_e32 v12, v12
	v_exp_f32_e32 v13, v13
	v_exp_f32_e32 v6, v6
	v_exp_f32_e32 v7, v7
	v_exp_f32_e32 v8, v8
	v_exp_f32_e32 v9, v9
	v_pk_add_f32 v[26:27], v[26:27], 1.0 op_sel_hi:[1,0]
	v_pk_add_f32 v[28:29], v[28:29], 1.0 op_sel_hi:[1,0]
	v_pk_add_f32 v[18:19], v[18:19], 1.0 op_sel_hi:[1,0]
	v_pk_add_f32 v[20:21], v[20:21], 1.0 op_sel_hi:[1,0]
	v_pk_add_f32 v[10:11], v[10:11], 1.0 op_sel_hi:[1,0]
	v_pk_add_f32 v[12:13], v[12:13], 1.0 op_sel_hi:[1,0]
	v_pk_add_f32 v[6:7], v[6:7], 1.0 op_sel_hi:[1,0]
	v_pk_add_f32 v[8:9], v[8:9], 1.0 op_sel_hi:[1,0]
	v_rcp_f32_e32 v26, v26
	v_rcp_f32_e32 v27, v27
	v_rcp_f32_e32 v28, v28
	v_rcp_f32_e32 v29, v29
	v_rcp_f32_e32 v18, v18
	v_rcp_f32_e32 v19, v19
	v_rcp_f32_e32 v20, v20
	v_rcp_f32_e32 v21, v21
	v_rcp_f32_e32 v10, v10
	v_rcp_f32_e32 v11, v11
	v_rcp_f32_e32 v12, v12
	v_rcp_f32_e32 v13, v13
	v_rcp_f32_e32 v6, v6
	v_rcp_f32_e32 v7, v7
	v_rcp_f32_e32 v8, v8
	v_rcp_f32_e32 v9, v9
	v_pk_mul_f32 v[30:31], v[30:31], v[26:27]
	v_pk_mul_f32 v[32:33], v[32:33], v[28:29]
	v_pk_mul_f32 v[22:23], v[22:23], v[18:19]
	v_pk_mul_f32 v[24:25], v[24:25], v[20:21]
	v_pk_mul_f32 v[14:15], v[14:15], v[10:11]
	v_pk_mul_f32 v[16:17], v[16:17], v[12:13]
	v_pk_mul_f32 v[2:3], v[2:3], v[6:7]
	v_pk_mul_f32 v[4:5], v[4:5], v[8:9]
	v_add_u32_e32 v150, 0xa0, v148
	v_mad_i64_i32 v[150:151], s[24:25], v150, s86, v[140:141]
	v_cvt_pk_bf16_f32 v156, v30, v31
	v_cvt_pk_bf16_f32 v157, v32, v33
	v_cvt_pk_bf16_f32 v158, v22, v23
	v_cvt_pk_bf16_f32 v159, v24, v25
	v_lshl_add_u64 v[150:151], v[150:151], 0, v[142:143]
	global_store_dwordx4 v[150:151], v[156:159], off
	v_add_u32_e32 v152, 0xb0, v148
	v_mad_i64_i32 v[152:153], s[24:25], v152, s86, v[140:141]
	v_cvt_pk_bf16_f32 v160, v14, v15
	v_cvt_pk_bf16_f32 v161, v16, v17
	v_cvt_pk_bf16_f32 v162, v2, v3
	v_cvt_pk_bf16_f32 v163, v4, v5
	v_lshl_add_u64 v[152:153], v[152:153], 0, v[142:143]
	global_store_dwordx4 v[152:153], v[160:163], off
	s_andn2_b64 vcc, exec, s[18:19]
	s_mov_b64 s[24:25], -1
	s_cbranch_vccnz .LBB0_367
	s_andn2_b64 vcc, exec, s[4:5]
	s_cbranch_vccnz .LBB0_366
	s_barrier
	s_branch .LBB0_366
